# attention softmax VALU trimmed: v_max x,x,x canonicalisations in front of row-max / running-max (inputs never signalling NaN) and the 0+p row-sum seed removed: 11 VALU fewer per iteration on the co-li
# baseline (speedup 1.0000x reference)
; __device__ __forceinline__ void finishSM(f32x16& p0, f32x16& p1, float alpha, float& l_reg, bf16x8& pa0, bf16x8& pa1, bf16x8& pa2, bf16x8& pa3) {
;     for (int r = 0; r < 16; ++r) p1[r] = __builtin_amdgcn_exp2f(p1[r]);
;     float ps = 0; for (int r = 0; r < 16; ++r) ps += p0[r]; for (int r = 0; r < 16; ++r) ps += p1[r];
;     { auto rr = __builtin_amdgcn_permlane32_swap(__float_as_uint(ps), __float_as_uint(ps), false, false);
;       ps = __uint_as_float(rr[0]) + __uint_as_float(rr[1]); }
;     l_reg = l_reg * alpha + ps;
;     ...
;     PK4(p0, 0, pa0); PK4(p0, 8, pa1); PK4(p1, 0, pa2); PK4(p1, 8, pa3);
; template <int KB>
; __device__ __forceinline__ void qkt(f32x16& p0, f32x16& p1, const char* K_lds, int r32, int hi, const bf16x8* qr) {
;     p0 = f32x16{}; p1 = f32x16{};
;     const char* kb[4];
; #pragma unroll
;     for (int dd = 0; dd < 4; ++dd) kb[dd] = K_lds + KB * SHM_K + KSWZ(r32, (dd * 16 + hi * 8) * 2);
; #pragma unroll
;     for (int d0 = 0; d0 < 8; ++d0) { const char* a = kb[d0 & 3] + (d0 >> 2) * 128;
;         bf16x8 b0 = *reinterpret_cast<const bf16x8*>(a);
;         bf16x8 b1 = *reinterpret_cast<const bf16x8*>(a + 32 * 256);
;         p0 = __builtin_amdgcn_mfma_f32_32x32x16_bf16(b0, qr[d0], p0, 0, 0, 0);
;         p1 = __builtin_amdgcn_mfma_f32_32x32x16_bf16(b1, qr[d0], p1, 0, 0, 0); }
; }
.LBB0_89:
	ds_read_b128 v[66:69], v169 offset:49152
	ds_read_b128 v[70:73], v169 offset:57344
	ds_read_b128 v[100:103], v193 offset:49152
	ds_read_b128 v[136:139], v193 offset:57344
	ds_read_b128 v[234:237], v194 offset:49152
	ds_read_b128 v[238:241], v194 offset:57344
	v_add_f32_e32 v148, v233, v231
	v_add_f32_e32 v148, v229, v148
	v_add_f32_e32 v148, v232, v148
	v_add_f32_e32 v148, v228, v148
	v_add_f32_e32 v148, v230, v148
	v_add_f32_e32 v148, v226, v148
	v_add_f32_e32 v148, v227, v148
	v_add_f32_e32 v148, v223, v148
	v_add_f32_e32 v148, v225, v148
	v_add_f32_e32 v148, v209, v148
	v_add_f32_e32 v148, v224, v148
	v_add_f32_e32 v148, v206, v148
	v_add_f32_e32 v148, v208, v148
	v_add_f32_e32 v148, v205, v148
	v_add_f32_e32 v148, v207, v148
	v_exp_f32_e32 v140, v152
	v_exp_f32_e32 v141, v153
	v_exp_f32_e32 v142, v180
	v_exp_f32_e32 v143, v181
	s_waitcnt lgkmcnt(5)
	v_mfma_f32_32x32x16_bf16 v[82:97], v[66:69], v[132:135], 0
	v_exp_f32_e32 v144, v160
	v_exp_f32_e32 v145, v161
	v_exp_f32_e32 v146, v154
	v_exp_f32_e32 v147, v155
	s_waitcnt lgkmcnt(4)
	v_mfma_f32_32x32x16_bf16 v[66:81], v[70:73], v[132:135], 0
	v_exp_f32_e32 v178, v178
	v_exp_f32_e32 v179, v179
	v_exp_f32_e32 v162, v162
	v_exp_f32_e32 v163, v163
	s_waitcnt lgkmcnt(3)
	v_mfma_f32_32x32x16_bf16 v[82:97], v[100:103], v[128:131], v[82:97]
	v_add_f32_e32 v148, v178, v148
	v_add_f32_e32 v148, v179, v148
	v_add_f32_e32 v148, v162, v148
	v_exp_f32_e32 v158, v158
	s_waitcnt lgkmcnt(2)
	v_mfma_f32_32x32x16_bf16 v[66:81], v[136:139], v[128:131], v[66:81]
	v_exp_f32_e32 v159, v159
	v_exp_f32_e32 v156, v156
	v_exp_f32_e32 v157, v157
	v_add_f32_e32 v148, v163, v148
	ds_read_b128 v[100:103], v195 offset:49152
	ds_read_b128 v[136:139], v195 offset:57344
	s_waitcnt lgkmcnt(3)
	v_mfma_f32_32x32x16_bf16 v[82:97], v[234:237], v[124:127], v[82:97]
	v_add_f32_e32 v148, v158, v148
	v_add_f32_e32 v148, v159, v148
	v_add_f32_e32 v148, v156, v148
	v_add_f32_e32 v148, v157, v148
	s_waitcnt lgkmcnt(2)
	v_mfma_f32_32x32x16_bf16 v[66:81], v[238:241], v[124:127], v[66:81]
	v_add_f32_e32 v148, v140, v148
	v_add_f32_e32 v148, v141, v148
	v_add_f32_e32 v148, v142, v148
	v_add_f32_e32 v148, v143, v148
	ds_read_b128 v[234:237], v169 offset:49280
	ds_read_b128 v[238:241], v169 offset:57472
	s_waitcnt lgkmcnt(3)
	v_mfma_f32_32x32x16_bf16 v[82:97], v[100:103], v[120:123], v[82:97]
	v_add_f32_e32 v148, v144, v148
	v_add_f32_e32 v148, v145, v148
	v_add_f32_e32 v148, v146, v148
	v_add_f32_e32 v199, v147, v148
	s_waitcnt lgkmcnt(2)
	v_mfma_f32_32x32x16_bf16 v[66:81], v[136:139], v[120:123], v[66:81]
	v_mov_b32_e32 v200, v199
	s_nop 1
	v_permlane32_swap_b32_e32 v199, v200
	v_cvt_pk_bf16_f32 v148, v231, v233
	v_cvt_pk_bf16_f32 v149, v229, v232
	v_cvt_pk_bf16_f32 v150, v228, v230
	ds_read_b128 v[100:103], v193 offset:49280
	ds_read_b128 v[136:139], v193 offset:57472
	s_waitcnt lgkmcnt(3)
	v_mfma_f32_32x32x16_bf16 v[82:97], v[234:237], v[116:119], v[82:97]
	v_cvt_pk_bf16_f32 v151, v226, v227
	v_cvt_pk_bf16_f32 v152, v223, v225
	v_cvt_pk_bf16_f32 v153, v209, v224
	s_waitcnt lgkmcnt(2)
	v_mfma_f32_32x32x16_bf16 v[66:81], v[238:241], v[116:119], v[66:81]
	v_cvt_pk_bf16_f32 v154, v206, v208
	v_cvt_pk_bf16_f32 v155, v205, v207
	v_cvt_pk_bf16_f32 v158, v158, v159
	ds_read_b128 v[234:237], v194 offset:49280
	ds_read_b128 v[238:241], v194 offset:57472
	s_waitcnt lgkmcnt(3)
	v_mfma_f32_32x32x16_bf16 v[82:97], v[100:103], v[112:115], v[82:97]
	v_cvt_pk_bf16_f32 v159, v156, v157
	v_cvt_pk_bf16_f32 v156, v178, v179
	v_cvt_pk_bf16_f32 v157, v162, v163
	s_waitcnt lgkmcnt(2)
	v_mfma_f32_32x32x16_bf16 v[66:81], v[136:139], v[112:115], v[66:81]
	v_cvt_pk_bf16_f32 v160, v140, v141
	v_cvt_pk_bf16_f32 v161, v142, v143
	v_cvt_pk_bf16_f32 v162, v144, v145
	ds_read_b128 v[100:103], v195 offset:49280
	ds_read_b128 v[136:139], v195 offset:57472
	ds_read_b64_tr_b16 v[172:173], v185 offset:0
	ds_read_b64_tr_b16 v[174:175], v185 offset:0x800
	ds_read_b64_tr_b16 v[202:203], v185 offset:0x1000
	ds_read_b64_tr_b16 v[204:205], v185 offset:0x1800
	ds_read_b64_tr_b16 v[206:207], v185 offset:0x2000
	ds_read_b64_tr_b16 v[208:209], v185 offset:0x2800
	ds_read_b64_tr_b16 v[224:225], v185 offset:0x3000
	ds_read_b64_tr_b16 v[226:227], v185 offset:0x3800
	s_waitcnt lgkmcnt(11)
	v_mfma_f32_32x32x16_bf16 v[82:97], v[234:237], v[108:111], v[82:97]
	v_cvt_pk_bf16_f32 v163, v146, v147
	s_nop 0
	v_permlane32_swap_b32_e32 v148, v150
	v_permlane32_swap_b32_e32 v149, v151
	s_waitcnt lgkmcnt(10)
	v_mfma_f32_32x32x16_bf16 v[66:81], v[238:241], v[108:111], v[66:81]
	v_permlane32_swap_b32_e32 v152, v154
	v_permlane32_swap_b32_e32 v153, v155
	v_permlane32_swap_b32_e32 v156, v158
	s_waitcnt lgkmcnt(9)
	v_mfma_f32_32x32x16_bf16 v[82:97], v[100:103], v[104:107], v[82:97]
	v_permlane32_swap_b32_e32 v157, v159
	v_permlane32_swap_b32_e32 v160, v162
	v_permlane32_swap_b32_e32 v161, v163
	s_waitcnt lgkmcnt(8)
	v_mfma_f32_32x32x16_bf16 v[66:81], v[136:139], v[104:107], v[66:81]
	v_add_u32_e32 v169, s100, v169
	v_add_u32_e32 v193, s100, v193
	v_add_u32_e32 v194, s100, v194
	v_add_u32_e32 v195, s100, v195
	s_sub_i32 s100, 0, s100
	s_sub_i32 m0, 0, s100
	s_max_i32 m0, m0, 0
	s_add_i32 m0, m0, s32
	s_add_i32 m0, m0, 0x4000
	s_nop 0
	global_load_lds_dwordx4 v[244:245], off
	s_add_i32 m0, m0, 0x2000
	s_nop 0
	global_load_lds_dwordx4 v[246:247], off
	v_lshl_add_u64 v[244:245], v[244:245], 0, v[250:251]
	v_lshl_add_u64 v[246:247], v[246:247], 0, v[250:251]
	s_sub_i32 m0, 0, s100
	s_max_i32 m0, m0, 0
	s_add_i32 m0, m0, s32
	s_add_i32 m0, m0, s32
	s_sub_i32 m0, m0, 0x10000
	s_nop 0
	global_load_lds_dwordx4 v[248:249], off
	s_add_i32 m0, m0, 896
	s_nop 0
	global_load_lds_dwordx4 v[248:249], off offset:128
	v_lshl_add_u64 v[248:249], v[248:249], 0, v[250:251]
	s_nop 0
	s_waitcnt lgkmcnt(6)
; __device__ __forceinline__ void mask_tile(f32x16& p0, f32x16& p1, int dq, unsigned W) {
;     const float NEG = -__builtin_inff();
; #pragma unroll
;     for (int r = 0; r < 16; ++r) {
;         const int c = (r & 3) + 8 * (r >> 2);
;         if ((unsigned)(dq - c) >= W) p0[r] = NEG;
;         if ((unsigned)(dq - c - 32) >= W) p1[r] = NEG;
;     }
; }
; template <int VB>
; __device__ __forceinline__ void pv_tile(f32x16* o, int vb0, bf16x8 pa0, bf16x8 pa1, bf16x8 pa2, bf16x8 pa3) {
;     ...
;     PV_D0(0); PV_D0(1); PV_D0(2); PV_D0(3);
	v_mfma_f32_32x32x16_bf16 v[50:65], v[148:151], v[172:175], v[50:65]
	ds_read_b64_tr_b16 v[172:173], v185 offset:0x200
	ds_read_b64_tr_b16 v[174:175], v185 offset:0xa00
	s_waitcnt lgkmcnt(6)
	v_mfma_f32_32x32x16_bf16 v[50:65], v[152:155], v[202:205], v[50:65]
	ds_read_b64_tr_b16 v[202:203], v185 offset:0x1200
	ds_read_b64_tr_b16 v[204:205], v185 offset:0x1a00
	s_waitcnt lgkmcnt(6)
	v_mfma_f32_32x32x16_bf16 v[50:65], v[156:159], v[206:209], v[50:65]
	ds_read_b64_tr_b16 v[206:207], v185 offset:0x2200
	ds_read_b64_tr_b16 v[208:209], v185 offset:0x2a00
	s_waitcnt lgkmcnt(6)
	v_mfma_f32_32x32x16_bf16 v[50:65], v[160:163], v[224:227], v[50:65]
	ds_read_b64_tr_b16 v[224:225], v185 offset:0x3200
	ds_read_b64_tr_b16 v[226:227], v185 offset:0x3a00
	s_waitcnt lgkmcnt(6)
	v_mfma_f32_32x32x16_bf16 v[34:49], v[148:151], v[172:175], v[34:49]
	ds_read_b64_tr_b16 v[172:173], v185 offset:0x400
	ds_read_b64_tr_b16 v[174:175], v185 offset:0xc00
	s_waitcnt lgkmcnt(6)
	v_mfma_f32_32x32x16_bf16 v[34:49], v[152:155], v[202:205], v[34:49]
	ds_read_b64_tr_b16 v[202:203], v185 offset:0x1400
	ds_read_b64_tr_b16 v[204:205], v185 offset:0x1c00
	s_waitcnt lgkmcnt(6)
	v_mfma_f32_32x32x16_bf16 v[34:49], v[156:159], v[206:209], v[34:49]
	ds_read_b64_tr_b16 v[206:207], v185 offset:0x2400
	ds_read_b64_tr_b16 v[208:209], v185 offset:0x2c00
	s_waitcnt lgkmcnt(6)
	v_mfma_f32_32x32x16_bf16 v[34:49], v[160:163], v[224:227], v[34:49]
	ds_read_b64_tr_b16 v[224:225], v185 offset:0x3400
	ds_read_b64_tr_b16 v[226:227], v185 offset:0x3c00
	s_waitcnt lgkmcnt(6)
	v_mfma_f32_32x32x16_bf16 v[18:33], v[148:151], v[172:175], v[18:33]
	ds_read_b64_tr_b16 v[172:173], v185 offset:0x600
	ds_read_b64_tr_b16 v[174:175], v185 offset:0xe00
	s_waitcnt lgkmcnt(6)
	v_mfma_f32_32x32x16_bf16 v[18:33], v[152:155], v[202:205], v[18:33]
	ds_read_b64_tr_b16 v[202:203], v185 offset:0x1600
	ds_read_b64_tr_b16 v[204:205], v185 offset:0x1e00
	s_waitcnt lgkmcnt(6)
	v_mfma_f32_32x32x16_bf16 v[18:33], v[156:159], v[206:209], v[18:33]
	ds_read_b64_tr_b16 v[206:207], v185 offset:0x2600
	ds_read_b64_tr_b16 v[208:209], v185 offset:0x2e00
	s_waitcnt lgkmcnt(6)
	v_mfma_f32_32x32x16_bf16 v[18:33], v[160:163], v[224:227], v[18:33]
	ds_read_b64_tr_b16 v[224:225], v185 offset:0x3600
	ds_read_b64_tr_b16 v[226:227], v185 offset:0x3e00
	s_waitcnt lgkmcnt(6)
	v_mfma_f32_32x32x16_bf16 v[2:17], v[148:151], v[172:175], v[2:17]
	s_cmp_le_i32 s7, s6
	s_waitcnt lgkmcnt(4)
	v_mfma_f32_32x32x16_bf16 v[2:17], v[152:155], v[202:205], v[2:17]
	s_waitcnt lgkmcnt(2)
	v_mfma_f32_32x32x16_bf16 v[2:17], v[156:159], v[206:209], v[2:17]
	s_waitcnt lgkmcnt(0)
	v_mfma_f32_32x32x16_bf16 v[2:17], v[160:163], v[224:227], v[2:17]
	s_cbranch_scc1 .LBB0_91
	v_add_u32_e32 v148, 0x4000007b, v197
	v_cmp_gt_u32_e32 vcc, 2.0, v148
	v_add_u32_e32 v148, 0x5b, v197
	s_nop 0
	v_cndmask_b32_e32 v82, v220, v82, vcc
	v_cmp_lt_u32_e32 vcc, s33, v148
	v_add_u32_e32 v148, 0x7a, v197
	s_nop 0
	v_cndmask_b32_e32 v66, v220, v66, vcc
	v_cmp_lt_u32_e32 vcc, s33, v148
	v_add_u32_e32 v148, 0x5a, v197
	s_nop 0
	v_cndmask_b32_e32 v83, v220, v83, vcc
	v_cmp_lt_u32_e32 vcc, s33, v148
	v_add_u32_e32 v148, 0x79, v197
	s_nop 0
	v_cndmask_b32_e32 v67, v220, v67, vcc
	v_cmp_lt_u32_e32 vcc, s33, v148
	v_add_u32_e32 v148, 0x59, v197
	s_nop 0
	v_cndmask_b32_e32 v84, v220, v84, vcc
	v_cmp_lt_u32_e32 vcc, s33, v148
	v_add_u32_e32 v148, 0x78, v197
	s_nop 0
	v_cndmask_b32_e32 v68, v220, v68, vcc
	v_cmp_lt_u32_e32 vcc, s33, v148
	v_add_u32_e32 v148, 0x58, v197
	s_nop 0
	v_cndmask_b32_e32 v85, v220, v85, vcc
	v_cmp_lt_u32_e32 vcc, s33, v148
	v_add_u32_e32 v148, 0x73, v197
	s_nop 0
	v_cndmask_b32_e32 v69, v220, v69, vcc
	v_cmp_lt_u32_e32 vcc, s33, v148
	v_add_u32_e32 v148, 0x53, v197
	s_nop 0
	v_cndmask_b32_e32 v86, v220, v86, vcc
	v_cmp_lt_u32_e32 vcc, s33, v148
	v_add_u32_e32 v148, 0x72, v197
	s_nop 0
	v_cndmask_b32_e32 v70, v220, v70, vcc
	v_cmp_lt_u32_e32 vcc, s33, v148
	v_add_u32_e32 v148, 0x52, v197
	s_nop 0
	v_cndmask_b32_e32 v87, v220, v87, vcc
	v_cmp_lt_u32_e32 vcc, s33, v148
	v_add_u32_e32 v148, 0x71, v197
	s_nop 0
	v_cndmask_b32_e32 v71, v220, v71, vcc
	v_cmp_lt_u32_e32 vcc, s33, v148
	v_add_u32_e32 v148, 0x51, v197
	s_nop 0
	v_cndmask_b32_e32 v88, v220, v88, vcc
	v_cmp_lt_u32_e32 vcc, s33, v148
	v_add_u32_e32 v148, 0x70, v197
	s_nop 0
	v_cndmask_b32_e32 v72, v220, v72, vcc
	v_cmp_lt_u32_e32 vcc, s33, v148
	v_add_u32_e32 v148, 0x50, v197
	s_nop 0
	v_cndmask_b32_e32 v89, v220, v89, vcc
	v_cmp_lt_u32_e32 vcc, s33, v148
	v_add_u32_e32 v148, 0x6b, v197
	s_nop 0
	v_cndmask_b32_e32 v73, v220, v73, vcc
	v_cmp_lt_u32_e32 vcc, s33, v148
	v_add_u32_e32 v148, 0x4b, v197
	s_nop 0
	v_cndmask_b32_e32 v90, v220, v90, vcc
	v_cmp_lt_u32_e32 vcc, s33, v148
	v_add_u32_e32 v148, 0x6a, v197
	s_nop 0
	v_cndmask_b32_e32 v74, v220, v74, vcc
	v_cmp_lt_u32_e32 vcc, s33, v148
	v_add_u32_e32 v148, 0x4a, v197
	s_nop 0
	v_cndmask_b32_e32 v91, v220, v91, vcc
	v_cmp_lt_u32_e32 vcc, s33, v148
	v_add_u32_e32 v148, 0x69, v197
	s_nop 0
	v_cndmask_b32_e32 v75, v220, v75, vcc
	v_cmp_lt_u32_e32 vcc, s33, v148
	v_add_u32_e32 v148, 0x49, v197
	s_nop 0
	v_cndmask_b32_e32 v92, v220, v92, vcc
	v_cmp_lt_u32_e32 vcc, s33, v148
	v_add_u32_e32 v148, 0x68, v197
	s_nop 0
	v_cndmask_b32_e32 v76, v220, v76, vcc
	v_cmp_lt_u32_e32 vcc, s33, v148
	v_add_u32_e32 v148, 0x48, v197
	s_nop 0
	v_cndmask_b32_e32 v93, v220, v93, vcc
	v_cmp_lt_u32_e32 vcc, s33, v148
	v_add_u32_e32 v148, 0x63, v197
	s_nop 0
	v_cndmask_b32_e32 v77, v220, v77, vcc
	v_cmp_lt_u32_e32 vcc, s33, v148
	v_add_u32_e32 v148, 0x43, v197
	s_nop 0
	v_cndmask_b32_e32 v94, v220, v94, vcc
	v_cmp_lt_u32_e32 vcc, s33, v148
	v_add_u32_e32 v148, 0x62, v197
	s_nop 0
	v_cndmask_b32_e32 v78, v220, v78, vcc
	v_cmp_lt_u32_e32 vcc, s33, v148
	v_add_u32_e32 v148, 0x42, v197
	s_nop 0
	v_cndmask_b32_e32 v95, v220, v95, vcc
	v_cmp_lt_u32_e32 vcc, s33, v148
	v_add_u32_e32 v148, 0x61, v197
	s_nop 0
	v_cndmask_b32_e32 v79, v220, v79, vcc
	v_cmp_lt_u32_e32 vcc, s33, v148
	v_add_u32_e32 v148, 0x41, v197
	s_nop 0
	v_cndmask_b32_e32 v96, v220, v96, vcc
	v_cmp_lt_u32_e32 vcc, s33, v148
	v_add_u32_e32 v148, 0x60, v197
	s_nop 0
	v_cndmask_b32_e32 v80, v220, v80, vcc
	v_cmp_lt_u32_e32 vcc, s33, v148
	v_add_u32_e32 v148, 64, v197
	s_nop 0
	v_cndmask_b32_e32 v97, v220, v97, vcc
	v_cmp_lt_u32_e32 vcc, s33, v148
	s_nop 1
	v_cndmask_b32_e32 v81, v220, v81, vcc
; __device__ __forceinline__ void partialSM(f32x16& p0, f32x16& p1, float& m_reg, float& mn, float& alpha, bool rs) {
;     float pmax = p0[0]; for (int r = 1; r < 16; ++r) pmax = fmaxf(pmax, p0[r]); for (int r = 0; r < 16; ++r) pmax = fmaxf(pmax, p1[r]);
;     if (!rs) pmax = -__builtin_inff();
;     { auto rr = __builtin_amdgcn_permlane32_swap(__float_as_uint(pmax), __float_as_uint(pmax), false, false);
;       pmax = fmaxf(__uint_as_float(rr[0]), __uint_as_float(rr[1])); }
;     constexpr float C2 = 1.4426950408889634f * SCALE;
;     if (__builtin_expect(__all((pmax - m_reg) * SCALE <= THR), 1)) { mn = m_reg; alpha = 1.f; }
;     else { mn = fmaxf(m_reg, pmax); alpha = __builtin_amdgcn_exp2f((m_reg - mn) * C2); m_reg = mn; }
.LBB0_91:
	s_add_i32 s0, s3, -2
	s_lshr_b32 s8, s0, 2
	s_cmp_ge_i32 s8, s44
	s_cselect_b64 s[0:1], -1, 0
	s_lshl_b32 s8, 1, s8
	v_and_b32_e32 v148, s8, v165
	v_cmp_ne_u32_e32 vcc, 0, v148
	v_max_f32_e32 v148, v82, v83
	v_max3_f32 v148, v148, v84, v85
	v_max3_f32 v148, v148, v86, v87
	v_max3_f32 v148, v148, v88, v89
	v_max3_f32 v148, v148, v90, v91
	v_max3_f32 v148, v148, v92, v93
	v_max3_f32 v148, v148, v94, v95
	v_max3_f32 v148, v148, v96, v97
	v_max3_f32 v148, v148, v66, v67
	v_max3_f32 v148, v148, v68, v69
	v_max3_f32 v148, v148, v70, v71
	v_max3_f32 v148, v148, v72, v73
	v_max3_f32 v148, v148, v74, v75
	v_max3_f32 v148, v148, v76, v77
	v_max3_f32 v148, v148, v78, v79
	s_or_b64 s[40:41], s[0:1], vcc
	v_max3_f32 v148, v148, v80, v81
	v_cndmask_b32_e64 v148, v220, v148, s[40:41]
	v_mov_b32_e32 v149, v148
	s_nop 1
	v_permlane32_swap_b32_e32 v148, v149
	v_max_f32_e32 v148, v148, v149
	v_sub_f32_e32 v149, v148, v198
	v_mul_f32_e32 v149, 0x3db504f3, v149
	v_cmp_ge_f32_e32 vcc, s91, v149
	v_max_f32_e32 v148, v198, v148
	v_sub_f32_e32 v149, v198, v148
	v_mul_f32_e32 v149, 0x3e0293ee, v149
	v_exp_f32_e32 v149, v149
	s_cmp_eq_u64 vcc, exec
	s_cselect_b64 s[42:43], -1, 0
	v_cndmask_b32_e64 v202, v149, 1.0, s[42:43]
	v_cmp_gt_f32_e32 vcc, 1.0, v202
	s_cbranch_vccz .LBB0_95
	s_and_saveexec_b64 s[0:1], s[38:39]
	ds_write_b32 v187, v202 offset:128
	s_or_b64 exec, exec, s[0:1]
	s_waitcnt lgkmcnt(0)
	ds_read_b128 v[150:153], v186 offset:224
	ds_read_b128 v[154:157], v186 offset:192
	ds_read_b128 v[158:161], v186 offset:160
	ds_read_b128 v[172:175], v186 offset:128
	s_waitcnt lgkmcnt(3)
	v_pk_mul_f32 v[64:65], v[64:65], v[152:153]
	s_waitcnt lgkmcnt(2)
	v_pk_mul_f32 v[60:61], v[60:61], v[156:157]
	s_waitcnt lgkmcnt(1)
	v_pk_mul_f32 v[56:57], v[56:57], v[160:161]
	s_waitcnt lgkmcnt(0)
	v_pk_mul_f32 v[52:53], v[52:53], v[174:175]
	v_pk_mul_f32 v[62:63], v[62:63], v[150:151]
	v_pk_mul_f32 v[58:59], v[58:59], v[154:155]
	v_pk_mul_f32 v[54:55], v[54:55], v[158:159]
	v_pk_mul_f32 v[50:51], v[50:51], v[172:173]
	v_pk_mul_f32 v[48:49], v[48:49], v[152:153]
	v_pk_mul_f32 v[44:45], v[44:45], v[156:157]
	v_pk_mul_f32 v[40:41], v[40:41], v[160:161]
	v_pk_mul_f32 v[36:37], v[36:37], v[174:175]
	v_pk_mul_f32 v[46:47], v[46:47], v[150:151]
	v_pk_mul_f32 v[42:43], v[42:43], v[154:155]
	v_pk_mul_f32 v[38:39], v[38:39], v[158:159]
	v_pk_mul_f32 v[34:35], v[34:35], v[172:173]
	v_pk_mul_f32 v[32:33], v[32:33], v[152:153]
	v_pk_mul_f32 v[28:29], v[28:29], v[156:157]
	v_pk_mul_f32 v[24:25], v[24:25], v[160:161]
	v_pk_mul_f32 v[20:21], v[20:21], v[174:175]
	v_pk_mul_f32 v[30:31], v[30:31], v[150:151]
	v_pk_mul_f32 v[26:27], v[26:27], v[154:155]
	v_pk_mul_f32 v[22:23], v[22:23], v[158:159]
	v_pk_mul_f32 v[18:19], v[18:19], v[172:173]
	v_pk_mul_f32 v[16:17], v[16:17], v[152:153]
	v_pk_mul_f32 v[12:13], v[12:13], v[156:157]
	v_pk_mul_f32 v[8:9], v[8:9], v[160:161]
	v_pk_mul_f32 v[4:5], v[4:5], v[174:175]
	v_pk_mul_f32 v[14:15], v[14:15], v[150:151]
	v_pk_mul_f32 v[10:11], v[10:11], v[154:155]
	v_pk_mul_f32 v[6:7], v[6:7], v[158:159]
	v_pk_mul_f32 v[2:3], v[2:3], v[172:173]

; __device__ __forceinline__ void partialSM(f32x16& p0, f32x16& p1, float& m_reg, float& mn, float& alpha, bool rs) {
;     float pmax = p0[0]; for (int r = 1; r < 16; ++r) pmax = fmaxf(pmax, p0[r]); for (int r = 0; r < 16; ++r) pmax = fmaxf(pmax, p1[r]);
;     if (!rs) pmax = -__builtin_inff();
;     { auto rr = __builtin_amdgcn_permlane32_swap(__float_as_uint(pmax), __float_as_uint(pmax), false, false);
;       pmax = fmaxf(__uint_as_float(rr[0]), __uint_as_float(rr[1])); }
;     constexpr float C2 = 1.4426950408889634f * SCALE;
;     if (__builtin_expect(__all((pmax - m_reg) * SCALE <= THR), 1)) { mn = m_reg; alpha = 1.f; }
;     else { mn = fmaxf(m_reg, pmax); alpha = __builtin_amdgcn_exp2f((m_reg - mn) * C2); m_reg = mn; }
.LBB0_99:
	s_add_i32 s0, s3, -1
	s_lshr_b32 s8, s0, 2
	s_cmp_ge_i32 s8, s44
	s_cselect_b64 s[0:1], -1, 0
	s_lshl_b32 s8, 1, s8
	v_and_b32_e32 v148, s8, v165
	v_cmp_ne_u32_e32 vcc, 0, v148
	v_max_f32_e32 v148, v82, v83
	v_max3_f32 v148, v148, v84, v85
	v_max3_f32 v148, v148, v86, v87
	v_max3_f32 v148, v148, v88, v89
	v_max3_f32 v148, v148, v90, v91
	v_max3_f32 v148, v148, v92, v93
	v_max3_f32 v148, v148, v94, v95
	v_max3_f32 v148, v148, v96, v97
	v_max3_f32 v148, v148, v66, v67
	v_max3_f32 v148, v148, v68, v69
	v_max3_f32 v148, v148, v70, v71
	v_max3_f32 v148, v148, v72, v73
	v_max3_f32 v148, v148, v74, v75
	v_max3_f32 v148, v148, v76, v77
	v_max3_f32 v148, v148, v78, v79
	v_max3_f32 v148, v148, v80, v81
	s_or_b64 s[40:41], s[0:1], vcc
	v_cndmask_b32_e64 v148, v220, v148, s[40:41]
	v_mov_b32_e32 v149, v148
	s_nop 1
	v_permlane32_swap_b32_e32 v148, v149
	v_max_f32_e32 v148, v148, v149
	v_sub_f32_e32 v149, v148, v179
	v_mul_f32_e32 v149, 0x3db504f3, v149
	v_cmp_ge_f32_e32 vcc, s91, v149
	s_cmp_eq_u64 vcc, exec
	s_cselect_b64 s[42:43], -1, 0
	s_andn2_b64 vcc, exec, s[22:23]
	s_cbranch_vccnz .LBB0_101
.LBB0_101:
	v_max_f32_e32 v100, v179, v148
	v_sub_f32_e32 v101, v179, v100
	v_mul_f32_e32 v101, 0x3e0293ee, v101
	v_exp_f32_e32 v101, v101
	s_nop 0
	v_cndmask_b32_e64 v201, v101, 1.0, s[42:43]
	v_cmp_gt_f32_e32 vcc, 1.0, v201
	s_cbranch_vccz .LBB0_105
	s_and_saveexec_b64 s[0:1], s[38:39]
	ds_write_b32 v187, v201 offset:128
	s_or_b64 exec, exec, s[0:1]
	s_waitcnt lgkmcnt(0)
	ds_read_b128 v[136:139], v186 offset:224
	ds_read_b128 v[140:143], v186 offset:192
	ds_read_b128 v[144:147], v186 offset:160
	ds_read_b128 v[148:151], v186 offset:128
	s_waitcnt lgkmcnt(3)
	v_pk_mul_f32 v[64:65], v[64:65], v[138:139]
	s_waitcnt lgkmcnt(2)
	v_pk_mul_f32 v[60:61], v[60:61], v[142:143]
	s_waitcnt lgkmcnt(1)
	v_pk_mul_f32 v[56:57], v[56:57], v[146:147]
	s_waitcnt lgkmcnt(0)
	v_pk_mul_f32 v[52:53], v[52:53], v[150:151]
	v_pk_mul_f32 v[62:63], v[62:63], v[136:137]
	v_pk_mul_f32 v[58:59], v[58:59], v[140:141]
	v_pk_mul_f32 v[54:55], v[54:55], v[144:145]
	v_pk_mul_f32 v[50:51], v[50:51], v[148:149]
	v_pk_mul_f32 v[48:49], v[48:49], v[138:139]
	v_pk_mul_f32 v[44:45], v[44:45], v[142:143]
	v_pk_mul_f32 v[40:41], v[40:41], v[146:147]
	v_pk_mul_f32 v[36:37], v[36:37], v[150:151]
	v_pk_mul_f32 v[46:47], v[46:47], v[136:137]
	v_pk_mul_f32 v[42:43], v[42:43], v[140:141]
	v_pk_mul_f32 v[38:39], v[38:39], v[144:145]
	v_pk_mul_f32 v[34:35], v[34:35], v[148:149]
	v_pk_mul_f32 v[32:33], v[32:33], v[138:139]
	v_pk_mul_f32 v[28:29], v[28:29], v[142:143]
	v_pk_mul_f32 v[24:25], v[24:25], v[146:147]
	v_pk_mul_f32 v[20:21], v[20:21], v[150:151]
	v_pk_mul_f32 v[30:31], v[30:31], v[136:137]
	v_pk_mul_f32 v[26:27], v[26:27], v[140:141]
	v_pk_mul_f32 v[22:23], v[22:23], v[144:145]
	v_pk_mul_f32 v[18:19], v[18:19], v[148:149]
	v_pk_mul_f32 v[16:17], v[16:17], v[138:139]
	v_pk_mul_f32 v[12:13], v[12:13], v[142:143]
	v_pk_mul_f32 v[8:9], v[8:9], v[146:147]
	v_pk_mul_f32 v[4:5], v[4:5], v[150:151]
	v_pk_mul_f32 v[14:15], v[14:15], v[136:137]
	v_pk_mul_f32 v[10:11], v[10:11], v[140:141]
	v_pk_mul_f32 v[6:7], v[6:7], v[144:145]
	v_pk_mul_f32 v[2:3], v[2:3], v[148:149]
